# baseline (speedup 1.0000x reference)
; __global__ void __launch_bounds__(256, 2) fwd_kernel(Params p) {
;     ...
;                 if (p.phase_lo < p.phase_hi) {
;                     unsigned* ctr = (unsigned*)(pq.ws + OFF_ctr) + l;
;                     for (;;) {
;                         if (threadIdx.x == 0) xb_st[2] = atomicAdd(ctr, 1u);
;                         __syncthreads();
;                         const int job = (int)xb_st[2];
;                         __syncthreads();
;                         if (job >= MIX_JOBS) break;
;                         mix_job(pq, l, job, qkb, smem);
.LBB0_945:
	s_setprio 0
	s_mov_b64 s[0:1], exec
	v_readlane_b32 s4, v251, 17
	v_readlane_b32 s5, v251, 18
	s_and_b64 s[4:5], s[0:1], s[4:5]
	s_mov_b64 exec, s[4:5]
	s_cbranch_execz .LBB0_947
	v_readlane_b32 s4, v254, 57
	v_readlane_b32 s5, v254, 58
	s_nop 1
	v_mov_b64_e32 v[0:1], s[4:5]
	s_waitcnt vmcnt(0)
	flat_atomic_add v0, v[0:1], v190 sc0
	v_readlane_b32 s4, v252, 25
	s_nop 1
	v_mov_b32_e32 v1, s4
	s_waitcnt vmcnt(0) lgkmcnt(0)
	ds_write_b32 v1, v0

; template <bool SB> ...
;     ...
;         __syncthreads();
;         if (early && (xflag[0] & xflag[1] & xflag[2] & xflag[3])) break;
;         *(uint4*)(sK + so0) = rk0; *(uint4*)(sK + so1) = rk1; *(uint4*)(sV + so0) = rv0; *(uint4*)(sV + so1) = rv1;
;         if (!SB && t < 64) sF[t] = rf * LOG2E;
;         __syncthreads();
;         if (kt > 0) {
;             const size_t kb = (size_t)(kt - 1) * 64;
;             const bf16_t* kp = Kp + (kb + srow) * ldk + sch * 8; rk0 = *(const uint4*)kp; rk1 = *(const uint4*)(kp + 8);
;             const bf16_t* vp = VT + (size_t)srow * ldvt + kb + sch * 8; rv0 = *(const uint4*)vp; rv1 = *(const uint4*)(vp + 8);
;             if (!SB && t < 64) rf = Fk[kb + t];
;         }
.LBB0_1691:
	s_setprio 2
	v_mov_b32_e32 v66, 0x4100
	s_waitcnt vmcnt(0) lgkmcnt(0)
	s_barrier
	ds_read_b128 v[66:69], v66
	s_or_b64 s[34:35], s[34:35], exec
	s_waitcnt lgkmcnt(0)
	v_and_b32_e32 v68, v66, v68
	v_bitop3_b32 v66, v68, v67, v69 bitop3:0x80
	v_cmp_eq_u32_e64 s[0:1], 0, v66
	s_and_saveexec_b64 s[38:39], s[0:1]
	s_cbranch_execz .LBB0_1690
	v_readlane_b32 s92, v252, 27
	v_readlane_b32 s93, v252, 28
	s_cmp_eq_u32 s92, -1
	ds_write_b128 v173, v[16:19]
	ds_write_b128 v174, v[20:23]
	ds_write_b128 v173, v[24:27] offset:8192
	ds_write_b128 v174, v[28:31] offset:8192
	s_waitcnt lgkmcnt(0)
	s_barrier
	s_cbranch_scc1 .LBB0_1694
	s_lshl_b64 s[0:1], s[92:93], 6
	v_lshl_add_u64 v[16:17], s[0:1], 0, v[100:101]
	v_lshlrev_b64 v[16:17], 9, v[16:17]
	s_lshl_b64 s[0:1], s[92:93], 7
	v_lshl_add_u64 v[20:21], v[102:103], 0, v[16:17]
	v_lshl_add_u64 v[28:29], v[104:105], 0, s[0:1]
	flat_load_dwordx4 v[16:19], v[20:21]
	s_nop 0
	flat_load_dwordx4 v[20:23], v[20:21] offset:16
	s_nop 0
	flat_load_dwordx4 v[24:27], v[28:29]
	s_nop 0
	flat_load_dwordx4 v[28:31], v[28:29] offset:16

; template <bool SB> ...
;     ...
;         __syncthreads();
;         if (early && (xflag[0] & xflag[1] & xflag[2] & xflag[3])) break;
;         *(uint4*)(sK + so0) = rk0; *(uint4*)(sK + so1) = rk1; *(uint4*)(sV + so0) = rv0; *(uint4*)(sV + so1) = rv1;
;         if (!SB && t < 64) sF[t] = rf * LOG2E;
;         __syncthreads();
.LBB0_1731:
	s_setprio 2
	v_cndmask_b32_e64 v0, 0, 1, s[26:27]
	v_cmp_ne_u32_e64 s[48:49], 1, v0
	s_andn2_b64 vcc, exec, s[26:27]
	s_mov_b64 s[16:17], s[56:57]
	s_barrier
	s_cbranch_vccnz .LBB0_1733
	v_mov_b32_e32 v0, 0x4100
	ds_read_b128 v[0:3], v0
	s_andn2_b64 s[0:1], s[56:57], exec
	s_waitcnt lgkmcnt(0)
	v_and_b32_e32 v2, v0, v2
	v_bitop3_b32 v0, v2, v1, v3 bitop3:0x80
	v_cmp_eq_u32_e32 vcc, 0, v0
	s_and_b64 s[14:15], vcc, exec
	s_or_b64 s[16:17], s[0:1], s[14:15]
